# P4 recurrence: the four serialized QA fragment reads of the second o-accumulator chain issued together (counted lgkmcnt)
# speedup vs baseline: 1.0027x; 1.0027x over previous
; #define LAS __attribute__((address_space(3)))
;     ...
;             for (int tb = 0; tb < 2; ++tb)
; #pragma unroll
;                 for (int kk = 0; kk < 4; ++kk) { const bf16x8_t a = *(const LAS bf16x8_t*)(QA + (16 * tb + fr) * 136 + 32 * kk + 8 * q); const bf16x8_t b = *(const LAS bf16x8_t*)(ST + (16 * w + fr) * 136 + 32 * kk + 8 * q);
;                     oacc[tb] = __builtin_amdgcn_mfma_f32_16x16x32_bf16(a, b, oacc[tb], 0, 0, 0); }
;         }
; #pragma unroll
;         for (int kb = 0; kb < 8; ++kb) { const f32x4 d4 = *(const LAS f32x4*)(DEC + 16 * kb + 4 * q); const bf16x8_t a = *(const LAS bf16x8_t*)(KDT + (16 * kb + fr) * 40 + 8 * q);
;             S[kb] = __builtin_amdgcn_mfma_f32_16x16x32_bf16(a, bV, S[kb] * d4, 0, 0, 0); }
.LBB0_586:
	ds_read_b128 v[108:111], v178
	v_add_u32_e32 v188, v154, v153
	ds_read_b128 v[112:115], v188 offset:37888
	ds_read_b128 v[190:193], v178 offset:64
	ds_read_b128 v[194:197], v188 offset:37952
	v_add_u32_e32 v186, 0, v155
	s_waitcnt lgkmcnt(2)
	v_mfma_f32_16x16x32_bf16 v[108:111], v[108:111], v[112:115], 0
	s_waitcnt lgkmcnt(0)
	v_mfma_f32_16x16x32_bf16 v[108:111], v[190:193], v[194:197], v[108:111]
	ds_read_b128 v[190:193], v178 offset:128
	ds_read_b128 v[204:207], v188 offset:38016
	s_waitcnt lgkmcnt(0)
	v_mfma_f32_16x16x32_bf16 v[108:111], v[190:193], v[204:207], v[108:111]
	ds_read_b128 v[190:193], v178 offset:192
	ds_read_b128 v[208:211], v188 offset:38080
	s_waitcnt lgkmcnt(0)
	v_mfma_f32_16x16x32_bf16 v[108:111], v[190:193], v[208:211], v[108:111]
	ds_read_b128 v[190:193], v178 offset:4352
	ds_read_b128 v[218:221], v178 offset:4416
	ds_read_b128 v[222:225], v178 offset:4480
	ds_read_b128 v[226:229], v178 offset:4544
	s_waitcnt lgkmcnt(3)
	v_mfma_f32_16x16x32_bf16 v[112:115], v[190:193], v[112:115], 0
	s_waitcnt lgkmcnt(2)
	v_mfma_f32_16x16x32_bf16 v[112:115], v[218:221], v[194:197], v[112:115]
	s_waitcnt lgkmcnt(1)
	v_mfma_f32_16x16x32_bf16 v[112:115], v[222:225], v[204:207], v[112:115]
	s_waitcnt lgkmcnt(0)
	v_mfma_f32_16x16x32_bf16 v[112:115], v[226:229], v[208:211], v[112:115]
	v_add_u32_e32 v191, 0x12e00, v186
	ds_read_b128 v[192:195], v191
	ds_read_b128 v[204:207], v179 offset:17408
	v_add_u32_e32 v190, 0x12e40, v186
	s_waitcnt lgkmcnt(1)
	v_pk_mul_f32 v[36:37], v[36:37], v[194:195]
	v_pk_mul_f32 v[34:35], v[34:35], v[192:193]
	s_waitcnt lgkmcnt(0)
	s_nop 0
	v_mfma_f32_16x16x32_bf16 v[34:37], v[204:207], v[104:107], v[34:37]
	ds_read_b128 v[192:195], v190
	ds_read_b128 v[204:207], v179 offset:18688
	s_waitcnt lgkmcnt(1)
	v_pk_mul_f32 v[40:41], v[40:41], v[194:195]
	v_pk_mul_f32 v[38:39], v[38:39], v[192:193]
	v_add_u32_e32 v192, 0x12e80, v186
	v_add_u32_e32 v193, 0x12ec0, v186
	s_waitcnt lgkmcnt(0)
	v_mfma_f32_16x16x32_bf16 v[38:41], v[204:207], v[104:107], v[38:41]
	ds_read_b128 v[194:197], v192
	ds_read_b128 v[204:207], v179 offset:19968
	s_waitcnt lgkmcnt(1)
	v_pk_mul_f32 v[44:45], v[44:45], v[196:197]
	v_pk_mul_f32 v[42:43], v[42:43], v[194:195]
	s_waitcnt lgkmcnt(0)
	s_nop 0
	v_mfma_f32_16x16x32_bf16 v[42:45], v[204:207], v[104:107], v[42:45]
	ds_read_b128 v[194:197], v193
	ds_read_b128 v[204:207], v179 offset:21248
	s_waitcnt lgkmcnt(1)
	v_pk_mul_f32 v[48:49], v[48:49], v[196:197]
	v_pk_mul_f32 v[46:47], v[46:47], v[194:195]
	v_add_u32_e32 v194, 0x12f00, v186
	v_add_u32_e32 v195, 0x12f40, v186
	s_waitcnt lgkmcnt(0)
	v_mfma_f32_16x16x32_bf16 v[46:49], v[204:207], v[104:107], v[46:49]
	ds_read_b128 v[204:207], v194
	ds_read_b128 v[208:211], v179 offset:22528
	v_add_u32_e32 v196, 0x12f80, v186
	v_add_u32_e32 v197, 0x12fc0, v186
	s_waitcnt lgkmcnt(1)
	v_pk_mul_f32 v[52:53], v[52:53], v[206:207]
	v_pk_mul_f32 v[50:51], v[50:51], v[204:205]
	s_waitcnt lgkmcnt(0)
	s_nop 0
	v_mfma_f32_16x16x32_bf16 v[50:53], v[208:211], v[104:107], v[50:53]
	ds_read_b128 v[204:207], v195
	ds_read_b128 v[208:211], v179 offset:23808
	s_waitcnt lgkmcnt(1)
	v_pk_mul_f32 v[56:57], v[56:57], v[206:207]
	v_pk_mul_f32 v[54:55], v[54:55], v[204:205]
	s_waitcnt lgkmcnt(0)
	s_nop 0
	v_mfma_f32_16x16x32_bf16 v[54:57], v[208:211], v[104:107], v[54:57]
	ds_read_b128 v[204:207], v196
	ds_read_b128 v[208:211], v179 offset:25088
	s_waitcnt lgkmcnt(1)
	v_pk_mul_f32 v[60:61], v[60:61], v[206:207]
	v_pk_mul_f32 v[58:59], v[58:59], v[204:205]
	s_waitcnt lgkmcnt(0)
	s_nop 0
	v_mfma_f32_16x16x32_bf16 v[58:61], v[208:211], v[104:107], v[58:61]
	ds_read_b128 v[204:207], v197
	ds_read_b128 v[208:211], v179 offset:26368
	s_waitcnt lgkmcnt(0)
	s_barrier
; #define LAS __attribute__((address_space(3)))
;     ...
;         __syncthreads();
;         if (FULL) {
; #pragma unroll
;             for (int tb = 0; tb < 2; ++tb) { const bf16x8_t a = *(const LAS bf16x8_t*)(Pm + (16 * tb + fr) * 40 + 8 * q); oacc[tb] = __builtin_amdgcn_mfma_f32_16x16x32_bf16(a, bV, oacc[tb], 0, 0, 0); }
;             if (VAR & 1) { asm volatile("" :: "v"(oacc[0]), "v"(oacc[1])); } else {
;             float ssv[8];
; #pragma unroll
;             for (int tb = 0; tb < 2; ++tb)
; #pragma unroll
;                 for (int r = 0; r < 4; ++r) ssv[tb * 4 + r] = dpp_xor_sum16(oacc[tb][r] * oacc[tb][r]);
;             if (fr == 0) {
; #pragma unroll
;                 for (int tb = 0; tb < 2; ++tb)
; #pragma unroll
;                     for (int r = 0; r < 4; ++r) SSQ[(16 * tb + 4 * q + r) * 8 + w] = ssv[tb * 4 + r]; }
	v_pk_mul_f32 v[64:65], v[64:65], v[206:207]
	v_pk_mul_f32 v[62:63], v[62:63], v[204:205]
	ds_read_b128 v[204:207], v180
	s_waitcnt lgkmcnt(0)
	v_mfma_f32_16x16x32_bf16 v[108:111], v[204:207], v[104:107], v[108:111]
	ds_read_b128 v[204:207], v180 offset:1280
	s_nop 6
	v_mul_f32_e32 v189, v111, v111
	v_mfma_f32_16x16x32_bf16 v[62:65], v[208:211], v[104:107], v[62:65]
	s_nop 0
	v_mov_b32_dpp v189, v189 quad_perm:[1,0,3,2] row_mask:0xf bank_mask:0xf bound_ctrl:1
	v_fmac_f32_e32 v189, v111, v111
	v_mul_f32_e32 v186, v110, v110
	s_waitcnt lgkmcnt(0)
	v_mfma_f32_16x16x32_bf16 v[104:107], v[204:207], v[104:107], v[112:115]
	v_add_f32_dpp v189, v189, v189 quad_perm:[2,3,0,1] row_mask:0xf bank_mask:0xf bound_ctrl:1
	v_mov_b32_dpp v186, v186 quad_perm:[1,0,3,2] row_mask:0xf bank_mask:0xf bound_ctrl:1
	s_nop 0
	v_mul_f32_e32 v112, v108, v108
	v_add_f32_dpp v204, v189, v189 row_half_mirror row_mask:0xf bank_mask:0xf bound_ctrl:1
	s_nop 2
	v_mul_f32_e32 v189, v104, v104
	v_mul_f32_e32 v114, v109, v109
	v_mov_b32_dpp v112, v112 quad_perm:[1,0,3,2] row_mask:0xf bank_mask:0xf bound_ctrl:1
	v_mov_b32_dpp v189, v189 quad_perm:[1,0,3,2] row_mask:0xf bank_mask:0xf bound_ctrl:1
	v_fmac_f32_e32 v189, v104, v104
	v_mov_b32_dpp v114, v114 quad_perm:[1,0,3,2] row_mask:0xf bank_mask:0xf bound_ctrl:1
	v_fmac_f32_e32 v112, v108, v108
	v_add_f32_dpp v189, v189, v189 quad_perm:[2,3,0,1] row_mask:0xf bank_mask:0xf bound_ctrl:1
	v_fmac_f32_e32 v114, v109, v109
	v_fmac_f32_e32 v186, v110, v110
	v_add_f32_dpp v206, v189, v189 row_half_mirror row_mask:0xf bank_mask:0xf bound_ctrl:1
	v_mul_f32_e32 v189, v105, v105
	v_add_f32_dpp v112, v112, v112 quad_perm:[2,3,0,1] row_mask:0xf bank_mask:0xf bound_ctrl:1
	v_add_f32_dpp v114, v114, v114 quad_perm:[2,3,0,1] row_mask:0xf bank_mask:0xf bound_ctrl:1
	v_mov_b32_dpp v189, v189 quad_perm:[1,0,3,2] row_mask:0xf bank_mask:0xf bound_ctrl:1
	v_fmac_f32_e32 v189, v105, v105
	v_add_f32_dpp v186, v186, v186 quad_perm:[2,3,0,1] row_mask:0xf bank_mask:0xf bound_ctrl:1
	v_add_f32_dpp v112, v112, v112 row_half_mirror row_mask:0xf bank_mask:0xf bound_ctrl:1
	v_add_f32_dpp v189, v189, v189 quad_perm:[2,3,0,1] row_mask:0xf bank_mask:0xf bound_ctrl:1
	v_add_f32_dpp v114, v114, v114 row_half_mirror row_mask:0xf bank_mask:0xf bound_ctrl:1
	v_add_f32_dpp v186, v186, v186 row_half_mirror row_mask:0xf bank_mask:0xf bound_ctrl:1
	v_add_f32_dpp v208, v189, v189 row_half_mirror row_mask:0xf bank_mask:0xf bound_ctrl:1
	v_mul_f32_e32 v189, v106, v106
	v_mov_b32_dpp v113, v112 row_mirror row_mask:0xf bank_mask:0xf bound_ctrl:1
	v_mov_b32_dpp v115, v114 row_mirror row_mask:0xf bank_mask:0xf bound_ctrl:1
	v_mov_b32_dpp v189, v189 quad_perm:[1,0,3,2] row_mask:0xf bank_mask:0xf bound_ctrl:1
	v_fmac_f32_e32 v189, v106, v106
	v_mov_b32_dpp v203, v186 row_mirror row_mask:0xf bank_mask:0xf bound_ctrl:1
	v_mov_b32_dpp v205, v204 row_mirror row_mask:0xf bank_mask:0xf bound_ctrl:1
	v_add_f32_dpp v189, v189, v189 quad_perm:[2,3,0,1] row_mask:0xf bank_mask:0xf bound_ctrl:1
	v_mov_b32_dpp v207, v206 row_mirror row_mask:0xf bank_mask:0xf bound_ctrl:1
	v_mov_b32_dpp v209, v208 row_mirror row_mask:0xf bank_mask:0xf bound_ctrl:1
	v_add_f32_dpp v210, v189, v189 row_half_mirror row_mask:0xf bank_mask:0xf bound_ctrl:1
	v_mul_f32_e32 v189, v107, v107
	s_nop 0
	v_mov_b32_dpp v211, v210 row_mirror row_mask:0xf bank_mask:0xf bound_ctrl:1
	v_mov_b32_dpp v189, v189 quad_perm:[1,0,3,2] row_mask:0xf bank_mask:0xf bound_ctrl:1
	v_fmac_f32_e32 v189, v107, v107
	s_nop 1
	v_add_f32_dpp v189, v189, v189 quad_perm:[2,3,0,1] row_mask:0xf bank_mask:0xf bound_ctrl:1
	s_nop 1
	v_add_f32_dpp v212, v189, v189 row_half_mirror row_mask:0xf bank_mask:0xf bound_ctrl:1
	v_add_u32_e32 v189, s3, v156
	s_nop 0
	v_mov_b32_dpp v213, v212 row_mirror row_mask:0xf bank_mask:0xf bound_ctrl:1
	s_and_saveexec_b64 vcc, s[10:11]
	s_cbranch_execz .LBB0_588
	v_add_f32_e32 v114, v114, v115
	v_add_f32_e32 v112, v112, v113
	v_add_f32_e32 v212, v212, v213
	v_add_f32_e32 v210, v210, v211
	v_add_f32_e32 v208, v208, v209
	v_add_f32_e32 v206, v206, v207
	v_add_f32_e32 v204, v204, v205
	v_add_f32_e32 v186, v186, v203
	ds_write2_b32 v189, v112, v114 offset1:8
	ds_write2_b32 v189, v186, v204 offset0:16 offset1:24
	ds_write2_b32 v189, v206, v208 offset0:128 offset1:136
	ds_write2_b32 v189, v210, v212 offset0:144 offset1:152

; #define LAS __attribute__((address_space(3)))
;     ...
;             for (int tb = 0; tb < 2; ++tb)
; #pragma unroll
;                 for (int kk = 0; kk < 4; ++kk) { const bf16x8_t a = *(const LAS bf16x8_t*)(QA + (16 * tb + fr) * 136 + 32 * kk + 8 * q); const bf16x8_t b = *(const LAS bf16x8_t*)(ST + (16 * w + fr) * 136 + 32 * kk + 8 * q);
;                     oacc[tb] = __builtin_amdgcn_mfma_f32_16x16x32_bf16(a, b, oacc[tb], 0, 0, 0); }
;         }
; #pragma unroll
;         for (int kb = 0; kb < 8; ++kb) { const f32x4 d4 = *(const LAS f32x4*)(DEC + 16 * kb + 4 * q); const bf16x8_t a = *(const LAS bf16x8_t*)(KDT + (16 * kb + fr) * 40 + 8 * q);
;             S[kb] = __builtin_amdgcn_mfma_f32_16x16x32_bf16(a, bV, S[kb] * d4, 0, 0, 0); }
.LBB0_631:
	ds_read_b128 v[108:111], v178
	ds_read_b128 v[112:115], v188 offset:37888
	ds_read_b128 v[202:205], v178 offset:64
	ds_read_b128 v[206:209], v188 offset:37952
	s_waitcnt lgkmcnt(2)
	v_mfma_f32_16x16x32_bf16 v[108:111], v[108:111], v[112:115], 0
	s_waitcnt lgkmcnt(0)
	v_mfma_f32_16x16x32_bf16 v[108:111], v[202:205], v[206:209], v[108:111]
	ds_read_b128 v[202:205], v178 offset:128
	ds_read_b128 v[210:213], v188 offset:38016
	s_waitcnt lgkmcnt(0)
	v_mfma_f32_16x16x32_bf16 v[108:111], v[202:205], v[210:213], v[108:111]
	ds_read_b128 v[202:205], v178 offset:192
	ds_read_b128 v[214:217], v188 offset:38080
	s_waitcnt lgkmcnt(0)
	v_mfma_f32_16x16x32_bf16 v[108:111], v[202:205], v[214:217], v[108:111]
	ds_read_b128 v[202:205], v178 offset:4352
	ds_read_b128 v[218:221], v178 offset:4416
	ds_read_b128 v[222:225], v178 offset:4480
	ds_read_b128 v[226:229], v178 offset:4544
	s_waitcnt lgkmcnt(3)
	v_mfma_f32_16x16x32_bf16 v[112:115], v[202:205], v[112:115], 0
	s_waitcnt lgkmcnt(2)
	v_mfma_f32_16x16x32_bf16 v[112:115], v[218:221], v[206:209], v[112:115]
	s_waitcnt lgkmcnt(1)
	v_mfma_f32_16x16x32_bf16 v[112:115], v[222:225], v[210:213], v[112:115]
	s_waitcnt lgkmcnt(0)
	v_mfma_f32_16x16x32_bf16 v[112:115], v[226:229], v[214:217], v[112:115]
	ds_read_b128 v[202:205], v191
	ds_read_b128 v[206:209], v179 offset:17408
	s_waitcnt lgkmcnt(1)
	v_pk_mul_f32 v[36:37], v[36:37], v[204:205]
	v_pk_mul_f32 v[34:35], v[34:35], v[202:203]
	s_waitcnt lgkmcnt(0)
	s_nop 0
	v_mfma_f32_16x16x32_bf16 v[34:37], v[206:209], v[104:107], v[34:37]
	ds_read_b128 v[202:205], v190
	ds_read_b128 v[206:209], v179 offset:18688
	s_waitcnt lgkmcnt(1)
	v_pk_mul_f32 v[40:41], v[40:41], v[204:205]
	v_pk_mul_f32 v[38:39], v[38:39], v[202:203]
	s_waitcnt lgkmcnt(0)
	s_nop 0
	v_mfma_f32_16x16x32_bf16 v[38:41], v[206:209], v[104:107], v[38:41]
	ds_read_b128 v[202:205], v192
	ds_read_b128 v[206:209], v179 offset:19968
	s_waitcnt lgkmcnt(1)
	v_pk_mul_f32 v[44:45], v[44:45], v[204:205]
	v_pk_mul_f32 v[42:43], v[42:43], v[202:203]
	ds_read_b128 v[190:193], v193
	ds_read_b128 v[202:205], v179 offset:21248
	s_waitcnt lgkmcnt(2)
	v_mfma_f32_16x16x32_bf16 v[42:45], v[206:209], v[104:107], v[42:45]
	s_waitcnt lgkmcnt(1)
	v_pk_mul_f32 v[48:49], v[48:49], v[192:193]
	v_pk_mul_f32 v[46:47], v[46:47], v[190:191]
	s_waitcnt lgkmcnt(0)
	s_nop 0
	v_mfma_f32_16x16x32_bf16 v[46:49], v[202:205], v[104:107], v[46:49]
	ds_read_b128 v[190:193], v194
	ds_read_b128 v[202:205], v179 offset:22528
	s_waitcnt lgkmcnt(1)
	v_pk_mul_f32 v[52:53], v[52:53], v[192:193]
	v_pk_mul_f32 v[50:51], v[50:51], v[190:191]
	s_waitcnt lgkmcnt(0)
	s_nop 0
	v_mfma_f32_16x16x32_bf16 v[50:53], v[202:205], v[104:107], v[50:53]
	ds_read_b128 v[190:193], v195
	ds_read_b128 v[202:205], v179 offset:23808
	s_waitcnt lgkmcnt(1)
	v_pk_mul_f32 v[56:57], v[56:57], v[192:193]
	v_pk_mul_f32 v[54:55], v[54:55], v[190:191]
	s_waitcnt lgkmcnt(0)
	s_nop 0
	v_mfma_f32_16x16x32_bf16 v[54:57], v[202:205], v[104:107], v[54:57]
	ds_read_b128 v[190:193], v196
	ds_read_b128 v[202:205], v179 offset:25088
	s_waitcnt lgkmcnt(1)
	v_pk_mul_f32 v[60:61], v[60:61], v[192:193]
	v_pk_mul_f32 v[58:59], v[58:59], v[190:191]
	ds_read_b128 v[190:193], v197
	ds_read_b128 v[194:197], v179 offset:26368
	s_waitcnt lgkmcnt(0)
	s_barrier
; #define LAS __attribute__((address_space(3)))
;     ...
;             for (int tb = 0; tb < 2; ++tb) { const bf16x8_t a = *(const LAS bf16x8_t*)(Pm + (16 * tb + fr) * 40 + 8 * q); oacc[tb] = __builtin_amdgcn_mfma_f32_16x16x32_bf16(a, bV, oacc[tb], 0, 0, 0); }
;             if (VAR & 1) { asm volatile("" :: "v"(oacc[0]), "v"(oacc[1])); } else {
;             float ssv[8];
; #pragma unroll
;             for (int tb = 0; tb < 2; ++tb)
; #pragma unroll
;                 for (int r = 0; r < 4; ++r) ssv[tb * 4 + r] = dpp_xor_sum16(oacc[tb][r] * oacc[tb][r]);
;             if (fr == 0) {
; #pragma unroll
;                 for (int tb = 0; tb < 2; ++tb)
; #pragma unroll
;                     for (int r = 0; r < 4; ++r) SSQ[(16 * tb + 4 * q + r) * 8 + w] = ssv[tb * 4 + r]; }
	v_pk_mul_f32 v[64:65], v[64:65], v[192:193]
	v_pk_mul_f32 v[62:63], v[62:63], v[190:191]
	ds_read_b128 v[190:193], v180
	s_waitcnt lgkmcnt(0)
	v_mfma_f32_16x16x32_bf16 v[108:111], v[190:193], v[104:107], v[108:111]
	ds_read_b128 v[190:193], v180 offset:1280
	s_nop 6
	v_mul_f32_e32 v188, v110, v110
	v_mfma_f32_16x16x32_bf16 v[58:61], v[202:205], v[104:107], v[58:61]
	s_nop 0
	v_mov_b32_dpp v188, v188 quad_perm:[1,0,3,2] row_mask:0xf bank_mask:0xf bound_ctrl:1
	v_fmac_f32_e32 v188, v110, v110
	v_mfma_f32_16x16x32_bf16 v[62:65], v[194:197], v[104:107], v[62:65]
	s_nop 0
	v_add_f32_dpp v188, v188, v188 quad_perm:[2,3,0,1] row_mask:0xf bank_mask:0xf bound_ctrl:1
	s_waitcnt lgkmcnt(0)
	v_mfma_f32_16x16x32_bf16 v[104:107], v[190:193], v[104:107], v[112:115]
	v_mul_f32_e32 v191, v111, v111
	v_add_f32_dpp v188, v188, v188 row_half_mirror row_mask:0xf bank_mask:0xf bound_ctrl:1
	s_nop 0
	v_mul_f32_e32 v112, v108, v108
	v_mul_f32_e32 v114, v109, v109
	s_nop 2
	v_mul_f32_e32 v193, v104, v104
	v_mul_f32_e32 v195, v105, v105
	v_mul_f32_e32 v197, v106, v106
	v_mul_f32_e32 v203, v107, v107
	v_mov_b32_dpp v112, v112 quad_perm:[1,0,3,2] row_mask:0xf bank_mask:0xf bound_ctrl:1
	v_mov_b32_dpp v114, v114 quad_perm:[1,0,3,2] row_mask:0xf bank_mask:0xf bound_ctrl:1
	v_mov_b32_dpp v191, v191 quad_perm:[1,0,3,2] row_mask:0xf bank_mask:0xf bound_ctrl:1
	v_mov_b32_dpp v193, v193 quad_perm:[1,0,3,2] row_mask:0xf bank_mask:0xf bound_ctrl:1
	v_mov_b32_dpp v195, v195 quad_perm:[1,0,3,2] row_mask:0xf bank_mask:0xf bound_ctrl:1
	v_mov_b32_dpp v197, v197 quad_perm:[1,0,3,2] row_mask:0xf bank_mask:0xf bound_ctrl:1
	v_mov_b32_dpp v203, v203 quad_perm:[1,0,3,2] row_mask:0xf bank_mask:0xf bound_ctrl:1
	v_fmac_f32_e32 v112, v108, v108
	v_fmac_f32_e32 v114, v109, v109
	v_fmac_f32_e32 v191, v111, v111
	v_fmac_f32_e32 v193, v104, v104
	v_fmac_f32_e32 v195, v105, v105
	v_fmac_f32_e32 v197, v106, v106
	v_fmac_f32_e32 v203, v107, v107
	v_add_f32_dpp v112, v112, v112 quad_perm:[2,3,0,1] row_mask:0xf bank_mask:0xf bound_ctrl:1
	v_add_f32_dpp v114, v114, v114 quad_perm:[2,3,0,1] row_mask:0xf bank_mask:0xf bound_ctrl:1
	v_add_f32_dpp v191, v191, v191 quad_perm:[2,3,0,1] row_mask:0xf bank_mask:0xf bound_ctrl:1
	v_add_f32_dpp v193, v193, v193 quad_perm:[2,3,0,1] row_mask:0xf bank_mask:0xf bound_ctrl:1
	v_add_f32_dpp v195, v195, v195 quad_perm:[2,3,0,1] row_mask:0xf bank_mask:0xf bound_ctrl:1
	v_add_f32_dpp v197, v197, v197 quad_perm:[2,3,0,1] row_mask:0xf bank_mask:0xf bound_ctrl:1
	v_add_f32_dpp v203, v203, v203 quad_perm:[2,3,0,1] row_mask:0xf bank_mask:0xf bound_ctrl:1
	v_add_f32_dpp v112, v112, v112 row_half_mirror row_mask:0xf bank_mask:0xf bound_ctrl:1
	v_add_f32_dpp v114, v114, v114 row_half_mirror row_mask:0xf bank_mask:0xf bound_ctrl:1
	v_add_f32_dpp v191, v191, v191 row_half_mirror row_mask:0xf bank_mask:0xf bound_ctrl:1
	v_add_f32_dpp v193, v193, v193 row_half_mirror row_mask:0xf bank_mask:0xf bound_ctrl:1
	v_add_f32_dpp v195, v195, v195 row_half_mirror row_mask:0xf bank_mask:0xf bound_ctrl:1
	v_add_f32_dpp v197, v197, v197 row_half_mirror row_mask:0xf bank_mask:0xf bound_ctrl:1
	v_add_f32_dpp v203, v203, v203 row_half_mirror row_mask:0xf bank_mask:0xf bound_ctrl:1
	v_mov_b32_dpp v113, v112 row_mirror row_mask:0xf bank_mask:0xf bound_ctrl:1
	v_mov_b32_dpp v115, v114 row_mirror row_mask:0xf bank_mask:0xf bound_ctrl:1
	v_mov_b32_dpp v190, v188 row_mirror row_mask:0xf bank_mask:0xf bound_ctrl:1
	v_mov_b32_dpp v192, v191 row_mirror row_mask:0xf bank_mask:0xf bound_ctrl:1
	v_mov_b32_dpp v194, v193 row_mirror row_mask:0xf bank_mask:0xf bound_ctrl:1
	v_mov_b32_dpp v196, v195 row_mirror row_mask:0xf bank_mask:0xf bound_ctrl:1
	v_mov_b32_dpp v202, v197 row_mirror row_mask:0xf bank_mask:0xf bound_ctrl:1
	v_mov_b32_dpp v204, v203 row_mirror row_mask:0xf bank_mask:0xf bound_ctrl:1
	s_and_saveexec_b64 s[26:27], s[10:11]
	s_cbranch_execz .LBB0_633
	v_add_f32_e32 v114, v114, v115
	v_add_f32_e32 v112, v112, v113
	v_add_f32_e32 v203, v203, v204
	v_add_f32_e32 v197, v197, v202
	v_add_f32_e32 v195, v195, v196
	v_add_f32_e32 v193, v193, v194
	v_add_f32_e32 v191, v191, v192
	v_add_f32_e32 v188, v188, v190
	ds_write2_b32 v189, v112, v114 offset1:8
	ds_write2_b32 v189, v188, v191 offset0:16 offset1:24
	ds_write2_b32 v189, v193, v195 offset0:128 offset1:136
	ds_write2_b32 v189, v197, v203 offset0:144 offset1:152
